# norm_rows (init): gain loads hoisted out of the row loop (was 8 load+store round trips per row)
# speedup vs baseline: 1.0024x; 1.0024x over previous
;     DI const float* in(int i) const { return (const float*)gp(i); }
; DI float wave_sum(float v) { v = half_sum(v); auto rr = __builtin_amdgcn_permlane32_swap(__float_as_uint(v), __float_as_uint(v), false, false); return __uint_as_float(rr[0]) + __uint_as_float(rr[1]); }
; DI int fresh_tid(const Params& P) { int t = P.tid; asm volatile("" : "+v"(t)); return t; }
; DI const float* xin_row(const Params& P, int t) { return t < 8192 ? P.in(0) + (size_t)t * DM : P.in(1) + (size_t)(t - 8192) * DM; }
; DI void norm_rows(const Params& P, int nrows, int srcsel  , const float* g, bf16_t* dst) {
;     const int tid_ = fresh_tid(P);
;     const int wid = tid_ >> 6, lane = tid_ & 63;
;     for (int t = blockIdx.x * 8 + wid; t < nrows; t += gridDim.x * 8) {
;         const float* src = srcsel == 0 ? xin_row(P, t) : (t < 512 ? P.in(2) + (size_t)t * DM : P.in(3) + (size_t)(t - 512) * DM);
;         f32x4 v[8]; float ss = 0.f;
; #pragma unroll
;         for (int j = 0; j < 8; ++j) { v[j] = *(const f32x4*)(src + j * 256 + lane * 4); ss += v[j][0] * v[j][0] + v[j][1] * v[j][1] + v[j][2] * v[j][2] + v[j][3] * v[j][3]; }
;         ss = wave_sum(ss); const float rn = rsqrtf(ss * (1.f / 2048.f) + EPS);
; #pragma unroll
;         for (int j = 0; j < 8; ++j) { const f32x4 gg = *(const f32x4*)(g + j * 256 + lane * 4);
.LBB0_522:
	v_readlane_b32 s0, v242, 11
	s_nop 1
	v_mov_b32_e32 v0, s0
	s_waitcnt vmcnt(7)
	ds_read_b64 v[2:3], v0
	v_mov_b32_e32 v0, v193
	v_readlane_b32 s0, v242, 6
	s_waitcnt lgkmcnt(0)
	v_readfirstlane_b32 s6, v2
	v_ashrrev_i32_e32 v2, 6, v0
	s_waitcnt vmcnt(2)
	v_add_u32_e32 v38, s0, v2
	s_movk_i32 s0, 0x4000
	v_readfirstlane_b32 s7, v3
	v_cmp_gt_i32_e32 vcc, s0, v38
	s_and_saveexec_b64 s[0:1], vcc
	s_cbranch_execz .LBB0_529
	v_lshlrev_b32_e32 v0, 2, v0
	v_and_b32_e32 v2, 0xfc, v0
	v_lshlrev_b32_e32 v0, 2, v2
	v_lshl_add_u64 v[40:41], s[6:7], 0, v[0:1]
	s_mov_b64 s[4:5], 0x1000
	v_lshl_add_u64 v[44:45], v[40:41], 0, s[4:5]
	s_mov_b64 s[4:5], 0x1400
	v_lshl_add_u64 v[46:47], v[40:41], 0, s[4:5]
	s_mov_b64 s[4:5], 0x1800
	v_lshlrev_b32_e32 v0, 1, v2
	v_lshl_add_u64 v[48:49], v[40:41], 0, s[4:5]
	s_mov_b64 s[4:5], 0x1c00
	v_lshl_add_u64 v[42:43], s[52:53], 0, v[0:1]
	s_waitcnt vmcnt(1)
	v_lshl_add_u64 v[50:51], v[40:41], 0, s[4:5]
	s_mov_b64 s[6:7], 0
	v_lshlrev_b32_e32 v0, 2, v2
	global_load_dwordx4 v[60:63], v[40:41], off
	global_load_dwordx4 v[64:67], v[40:41], off offset:1024
	global_load_dwordx4 v[68:71], v[40:41], off offset:2048
	global_load_dwordx4 v[72:75], v[40:41], off offset:3072
	global_load_dwordx4 v[76:79], v[44:45], off
	global_load_dwordx4 v[80:83], v[46:47], off
	global_load_dwordx4 v[84:87], v[48:49], off
	global_load_dwordx4 v[88:91], v[50:51], off
	s_waitcnt vmcnt(0)
	s_branch .LBB0_525
;     DI const float* in(int i) const { return (const float*)gp(i); }
; DI unsigned cvtpk(float lo, float hi) { unsigned r; asm volatile("v_cvt_pk_bf16_f32 %0, %1, %2" : "=v"(r) : "v"(lo), "v"(hi)); return r; }
; DI float wave_sum(float v) { v = half_sum(v); auto rr = __builtin_amdgcn_permlane32_swap(__float_as_uint(v), __float_as_uint(v), false, false); return __uint_as_float(rr[0]) + __uint_as_float(rr[1]); }
; DI const float* xin_row(const Params& P, int t) { return t < 8192 ? P.in(0) + (size_t)t * DM : P.in(1) + (size_t)(t - 8192) * DM; }
; DI void norm_rows(const Params& P, int nrows, int srcsel  , const float* g, bf16_t* dst) {
;     ...
;     for (int t = blockIdx.x * 8 + wid; t < nrows; t += gridDim.x * 8) {
;         const float* src = srcsel == 0 ? xin_row(P, t) : (t < 512 ? P.in(2) + (size_t)t * DM : P.in(3) + (size_t)(t - 512) * DM);
;         f32x4 v[8]; float ss = 0.f;
; #pragma unroll
;         for (int j = 0; j < 8; ++j) { v[j] = *(const f32x4*)(src + j * 256 + lane * 4); ss += v[j][0] * v[j][0] + v[j][1] * v[j][1] + v[j][2] * v[j][2] + v[j][3] * v[j][3]; }
;         ss = wave_sum(ss); const float rn = rsqrtf(ss * (1.f / 2048.f) + EPS);
; #pragma unroll
;         for (int j = 0; j < 8; ++j) { const f32x4 gg = *(const f32x4*)(g + j * 256 + lane * 4);
;             u32x2 w; w.x = cvtpk(v[j][0] * rn * gg[0], v[j][1] * rn * gg[1]); w.y = cvtpk(v[j][2] * rn * gg[2], v[j][3] * rn * gg[3]);
;             *(u32x2*)(dst + (size_t)t * DM + j * 256 + lane * 4) = w; }
.LBB0_524:
	s_or_b64 exec, exec, s[52:53]
	v_lshlrev_b64 v[2:3], 13, v[2:3]
	v_lshl_add_u64 v[2:3], v[4:5], 0, v[2:3]
	v_lshl_add_u64 v[2:3], v[2:3], 0, v[0:1]
	global_load_dwordx4 v[30:33], v[2:3], off
	global_load_dwordx4 v[26:29], v[2:3], off offset:1024
	global_load_dwordx4 v[22:25], v[2:3], off offset:2048
	global_load_dwordx4 v[18:21], v[2:3], off offset:3072
	v_add_co_u32_e32 v2, vcc, s78, v2
	s_waitcnt vmcnt(3)
	v_mul_f32_e32 v4, v31, v31
	v_addc_co_u32_e32 v3, vcc, 0, v3, vcc
	global_load_dwordx4 v[14:17], v[2:3], off
	global_load_dwordx4 v[10:13], v[2:3], off offset:1024
	global_load_dwordx4 v[6:9], v[2:3], off offset:2048
	s_waitcnt vmcnt(5)
	v_mul_f32_e32 v5, v27, v27
	v_fmac_f32_e32 v4, v30, v30
	v_fmac_f32_e32 v5, v26, v26
	v_fmac_f32_e32 v4, v32, v32
	v_fmac_f32_e32 v5, v28, v28
	v_fmac_f32_e32 v4, v33, v33
	v_fmac_f32_e32 v5, v29, v29
	v_add_f32_e32 v4, v4, v5
	s_waitcnt vmcnt(4)
	v_mul_f32_e32 v5, v23, v23
	v_fmac_f32_e32 v5, v22, v22
	v_fmac_f32_e32 v5, v24, v24
	v_fmac_f32_e32 v5, v25, v25
	v_add_f32_e32 v4, v4, v5
	s_waitcnt vmcnt(3)
	v_mul_f32_e32 v5, v19, v19
	v_fmac_f32_e32 v5, v18, v18
	v_fmac_f32_e32 v5, v20, v20
	v_fmac_f32_e32 v5, v21, v21
	v_add_f32_e32 v4, v4, v5
	s_waitcnt vmcnt(2)
	v_mul_f32_e32 v5, v15, v15
	v_fmac_f32_e32 v5, v14, v14
	v_fmac_f32_e32 v5, v16, v16
	v_fmac_f32_e32 v5, v17, v17
	v_add_f32_e32 v4, v4, v5
	s_waitcnt vmcnt(1)
	v_mul_f32_e32 v5, v11, v11
	v_fmac_f32_e32 v5, v10, v10
	v_fmac_f32_e32 v5, v12, v12
	v_fmac_f32_e32 v5, v13, v13
	v_add_f32_e32 v4, v4, v5
	s_waitcnt vmcnt(0)
	v_mul_f32_e32 v5, v7, v7
	v_fmac_f32_e32 v5, v6, v6
	v_fmac_f32_e32 v5, v8, v8
	v_fmac_f32_e32 v5, v9, v9
	v_add_f32_e32 v34, v4, v5
	global_load_dwordx4 v[2:5], v[2:3], off offset:3072
	s_waitcnt vmcnt(0)
	v_mul_f32_e32 v35, v3, v3
	v_fmac_f32_e32 v35, v2, v2
	v_fmac_f32_e32 v35, v4, v4
	v_fmac_f32_e32 v35, v5, v5
	v_add_f32_e32 v34, v34, v35
	ds_swizzle_b32 v35, v34 offset:swizzle(SWAP,16)
	s_waitcnt lgkmcnt(0)
	v_add_f32_e32 v34, v34, v35
	ds_swizzle_b32 v35, v34 offset:swizzle(SWAP,8)
	s_waitcnt lgkmcnt(0)
	v_add_f32_e32 v34, v34, v35
	ds_swizzle_b32 v35, v34 offset:swizzle(SWAP,4)
	s_waitcnt lgkmcnt(0)
	v_add_f32_e32 v34, v34, v35
	ds_swizzle_b32 v35, v34 offset:swizzle(SWAP,2)
	s_waitcnt lgkmcnt(0)
	v_add_f32_e32 v34, v34, v35
	ds_swizzle_b32 v35, v34 offset:swizzle(SWAP,1)
	s_waitcnt lgkmcnt(0)
	v_add_f32_e32 v34, v34, v35
	v_mov_b32_e32 v35, v34
	s_nop 1
	v_permlane32_swap_b32_e32 v34, v35
	v_add_f32_e32 v34, v34, v35
	v_fmamk_f32 v34, v34, 0x3a000000, v185
	v_cmp_gt_f32_e32 vcc, s95, v34
	v_mul_f32_e32 v35, 0x4b800000, v34
	s_nop 0
	v_cndmask_b32_e32 v34, v34, v35, vcc
	v_rsq_f32_e32 v34, v34
	s_nop 0
	v_mul_f32_e32 v35, 0x45800000, v34
	v_cndmask_b32_e32 v54, v34, v35, vcc
	v_lshlrev_b64 v[34:35], 12, v[38:39]
	v_lshl_add_u64 v[52:53], v[42:43], 0, v[34:35]
	v_mov_b32_e32 v34, v60
	v_mov_b32_e32 v35, v61
	v_mov_b32_e32 v36, v62
	v_mov_b32_e32 v37, v63
	v_mul_f32_e32 v30, v30, v54
	v_mul_f32_e32 v31, v31, v54
	v_mul_f32_e32 v26, v26, v54
	v_mul_f32_e32 v27, v27, v54
	v_mul_f32_e32 v22, v22, v54
	v_mul_f32_e32 v23, v23, v54
	v_mul_f32_e32 v18, v18, v54
	v_mul_f32_e32 v19, v19, v54
	v_mul_f32_e32 v14, v14, v54
	v_mul_f32_e32 v15, v15, v54
	v_mul_f32_e32 v10, v10, v54
	v_mul_f32_e32 v11, v11, v54
	v_mul_f32_e32 v6, v6, v54
	v_mul_f32_e32 v7, v7, v54
	v_mul_f32_e32 v2, v2, v54
	v_mul_f32_e32 v3, v3, v54
	v_add_u32_e32 v38, s87, v38
	v_cmp_lt_i32_e32 vcc, s82, v38
	s_or_b64 s[6:7], vcc, s[6:7]
	s_waitcnt vmcnt(0)
	v_mul_f32_e32 v30, v34, v30
	v_mul_f32_e32 v31, v35, v31
	v_cvt_pk_bf16_f32 v30, v30, v31
	v_mul_f32_e32 v31, v32, v54
	v_mul_f32_e32 v31, v36, v31
	v_mul_f32_e32 v32, v33, v54
	v_mul_f32_e32 v32, v37, v32
	v_cvt_pk_bf16_f32 v31, v31, v32
	global_store_dwordx2 v[52:53], v[30:31], off
	v_mov_b32_e32 v30, v64
	v_mov_b32_e32 v31, v65
	v_mov_b32_e32 v32, v66
	v_mov_b32_e32 v33, v67
	v_mul_f32_e32 v26, v30, v26
	v_mul_f32_e32 v27, v31, v27
	v_cvt_pk_bf16_f32 v26, v26, v27
	v_mul_f32_e32 v27, v28, v54
	v_mul_f32_e32 v27, v32, v27
	v_mul_f32_e32 v28, v29, v54
	v_mul_f32_e32 v28, v33, v28
	v_cvt_pk_bf16_f32 v27, v27, v28
	global_store_dwordx2 v[52:53], v[26:27], off offset:512
	v_mov_b32_e32 v26, v68
	v_mov_b32_e32 v27, v69
	v_mov_b32_e32 v28, v70
	v_mov_b32_e32 v29, v71
	v_mul_f32_e32 v22, v26, v22
	v_mul_f32_e32 v23, v27, v23
	v_cvt_pk_bf16_f32 v22, v22, v23
	v_mul_f32_e32 v23, v24, v54
	v_mul_f32_e32 v23, v28, v23
	v_mul_f32_e32 v24, v25, v54
	v_mul_f32_e32 v24, v29, v24
	v_cvt_pk_bf16_f32 v23, v23, v24
	global_store_dwordx2 v[52:53], v[22:23], off offset:1024
	v_mov_b32_e32 v22, v72
	v_mov_b32_e32 v23, v73
	v_mov_b32_e32 v24, v74
	v_mov_b32_e32 v25, v75
	v_mul_f32_e32 v18, v18, v22
	v_mul_f32_e32 v19, v19, v23
	v_cvt_pk_bf16_f32 v18, v18, v19
	v_mul_f32_e32 v19, v20, v54
	v_mul_f32_e32 v19, v19, v24
	v_mul_f32_e32 v20, v21, v54
	v_mul_f32_e32 v20, v20, v25
	v_cvt_pk_bf16_f32 v19, v19, v20
	global_store_dwordx2 v[52:53], v[18:19], off offset:1536
	v_mov_b32_e32 v18, v76
	v_mov_b32_e32 v19, v77
	v_mov_b32_e32 v20, v78
	v_mov_b32_e32 v21, v79
	v_mul_f32_e32 v14, v14, v18
	v_mul_f32_e32 v15, v15, v19
	v_cvt_pk_bf16_f32 v14, v14, v15
	v_mul_f32_e32 v15, v16, v54
	v_mul_f32_e32 v15, v15, v20
	v_mul_f32_e32 v16, v17, v54
	v_mul_f32_e32 v16, v16, v21
	v_cvt_pk_bf16_f32 v15, v15, v16
	global_store_dwordx2 v[52:53], v[14:15], off offset:2048
	v_mov_b32_e32 v14, v80
	v_mov_b32_e32 v15, v81
	v_mov_b32_e32 v16, v82
	v_mov_b32_e32 v17, v83
	v_mul_f32_e32 v10, v10, v14
	v_mul_f32_e32 v11, v11, v15
	v_cvt_pk_bf16_f32 v10, v10, v11
	v_mul_f32_e32 v11, v12, v54
	v_mul_f32_e32 v11, v11, v16
	v_mul_f32_e32 v12, v13, v54
	v_mul_f32_e32 v12, v12, v17
	v_cvt_pk_bf16_f32 v11, v11, v12
	global_store_dwordx2 v[52:53], v[10:11], off offset:2560
	v_mov_b32_e32 v10, v84
	v_mov_b32_e32 v11, v85
	v_mov_b32_e32 v12, v86
	v_mov_b32_e32 v13, v87
	v_mul_f32_e32 v6, v6, v10
	v_mul_f32_e32 v7, v7, v11
	v_cvt_pk_bf16_f32 v6, v6, v7
	v_mul_f32_e32 v7, v8, v54
	v_mul_f32_e32 v7, v7, v12
	v_mul_f32_e32 v8, v9, v54
	v_mul_f32_e32 v8, v8, v13
	v_cvt_pk_bf16_f32 v7, v7, v8
	global_store_dwordx2 v[52:53], v[6:7], off offset:3072
	v_mov_b32_e32 v6, v88
	v_mov_b32_e32 v7, v89
	v_mov_b32_e32 v8, v90
	v_mov_b32_e32 v9, v91
	v_mul_f32_e32 v2, v2, v6
	v_mul_f32_e32 v3, v3, v7
	v_cvt_pk_bf16_f32 v2, v2, v3
	v_mul_f32_e32 v3, v4, v54
	v_mul_f32_e32 v3, v3, v8
	v_mul_f32_e32 v4, v5, v54
	v_mul_f32_e32 v4, v4, v9
	v_cvt_pk_bf16_f32 v3, v3, v4
	global_store_dwordx2 v[52:53], v[2:3], off offset:3584
	s_andn2_b64 exec, exec, s[6:7]
	s_cbranch_execz .LBB0_529
